# startup phase_mod: SiLU preload loads batched (10 in flight) and adaLN GEMV k-loop software-pipelined with two load sets (16 row loads in flight)
# speedup vs baseline: 1.0106x; 1.0063x over previous
; __device__ __forceinline__ float siluf_(float x) { return x * rcpf_(1.f + __expf(-x)); }
; __device__ __forceinline__ void phase_mod(const PP& p, float* sm) {
;     ...
;     for (int i = tid; i < 5 * 1024; i += 512) { const int v = i >> 10, k = i & 1023; const float x = v < 4 ? p.in[I_C][v * 1024 + k] : p.in[I_CCTX][k]; sv[i] = siluf_(x); }
.LBB0_6:
	s_or_b64 exec, exec, s[0:1]
	s_andn2_b32 s8, s8, 63
	v_add_u32_e32 v162, s8, v163
	v_mov_b32_e32 v2, v162
	s_movk_i32 s0, 0x1400
	s_nop 0
	v_cmp_gt_i32_e32 vcc, s0, v2
	s_and_saveexec_b64 s[0:1], vcc
	s_cbranch_execz .LBB0_13
	s_add_i32 s11, 0, 0x27c18
	s_add_i32 s18, 0, 0x27c08
	v_mov_b32_e32 v6, s18
	v_mov_b32_e32 v7, s11
	ds_read_b64 v[8:9], v6
	ds_read_b64 v[10:11], v7
	v_lshlrev_b32_e32 v4, 2, v2
	v_mov_b32_e32 v5, 0
	v_lshl_add_u32 v3, v2, 2, 0
	s_mov_b64 s[6:7], 0x1000
	s_mov_b64 s[8:9], 0x3000
	s_waitcnt lgkmcnt(0)
	v_readfirstlane_b32 s22, v8
	v_readfirstlane_b32 s23, v9
	v_readfirstlane_b32 s4, v10
	v_readfirstlane_b32 s5, v11
	s_nop 1
	v_lshl_add_u64 v[12:13], s[22:23], 0, v[4:5]
	v_lshl_add_u64 v[14:15], s[4:5], 0, v[4:5]
	v_lshl_add_u64 v[16:17], v[12:13], 0, s[6:7]
	v_lshl_add_u64 v[18:19], v[12:13], 0, s[8:9]
	global_load_dword v20, v[16:17], off offset:-4096
	global_load_dword v21, v[16:17], off offset:-2048
	global_load_dword v22, v[16:17], off
	global_load_dword v23, v[16:17], off offset:2048
	global_load_dword v24, v[18:19], off offset:-4096
	global_load_dword v25, v[18:19], off offset:-2048
	global_load_dword v26, v[18:19], off
	global_load_dword v27, v[18:19], off offset:2048
	global_load_dword v28, v[14:15], off
	global_load_dword v29, v[14:15], off offset:2048
	s_waitcnt vmcnt(9)
	v_mul_f32_e32 v30, 0xbfb8aa3b, v20
	v_exp_f32_e32 v30, v30
	s_nop 0
	v_add_f32_e32 v30, 1.0, v30
	v_rcp_f32_e32 v30, v30
	s_nop 0
	v_mul_f32_e32 v20, v20, v30
	ds_write_b32 v3, v20
	s_waitcnt vmcnt(8)
	v_mul_f32_e32 v31, 0xbfb8aa3b, v21
	v_exp_f32_e32 v31, v31
	s_nop 0
	v_add_f32_e32 v31, 1.0, v31
	v_rcp_f32_e32 v31, v31
	s_nop 0
	v_mul_f32_e32 v21, v21, v31
	ds_write_b32 v3, v21 offset:2048
	s_waitcnt vmcnt(7)
	v_mul_f32_e32 v32, 0xbfb8aa3b, v22
	v_exp_f32_e32 v32, v32
	s_nop 0
	v_add_f32_e32 v32, 1.0, v32
	v_rcp_f32_e32 v32, v32
	s_nop 0
	v_mul_f32_e32 v22, v22, v32
	ds_write_b32 v3, v22 offset:4096
	s_waitcnt vmcnt(6)
	v_mul_f32_e32 v33, 0xbfb8aa3b, v23
	v_exp_f32_e32 v33, v33
	s_nop 0
	v_add_f32_e32 v33, 1.0, v33
	v_rcp_f32_e32 v33, v33
	s_nop 0
	v_mul_f32_e32 v23, v23, v33
	ds_write_b32 v3, v23 offset:6144
	s_waitcnt vmcnt(5)
	v_mul_f32_e32 v34, 0xbfb8aa3b, v24
	v_exp_f32_e32 v34, v34
	s_nop 0
	v_add_f32_e32 v34, 1.0, v34
	v_rcp_f32_e32 v34, v34
	s_nop 0
	v_mul_f32_e32 v24, v24, v34
	ds_write_b32 v3, v24 offset:8192
	s_waitcnt vmcnt(4)
	v_mul_f32_e32 v35, 0xbfb8aa3b, v25
	v_exp_f32_e32 v35, v35
	s_nop 0
	v_add_f32_e32 v35, 1.0, v35
	v_rcp_f32_e32 v35, v35
	s_nop 0
	v_mul_f32_e32 v25, v25, v35
	ds_write_b32 v3, v25 offset:10240
	s_waitcnt vmcnt(3)
	v_mul_f32_e32 v36, 0xbfb8aa3b, v26
	v_exp_f32_e32 v36, v36
	s_nop 0
	v_add_f32_e32 v36, 1.0, v36
	v_rcp_f32_e32 v36, v36
	s_nop 0
	v_mul_f32_e32 v26, v26, v36
	ds_write_b32 v3, v26 offset:12288
	s_waitcnt vmcnt(2)
	v_mul_f32_e32 v37, 0xbfb8aa3b, v27
	v_exp_f32_e32 v37, v37
	s_nop 0
	v_add_f32_e32 v37, 1.0, v37
	v_rcp_f32_e32 v37, v37
	s_nop 0
	v_mul_f32_e32 v27, v27, v37
	ds_write_b32 v3, v27 offset:14336
	s_waitcnt vmcnt(1)
	v_mul_f32_e32 v38, 0xbfb8aa3b, v28
	v_exp_f32_e32 v38, v38
	s_nop 0
	v_add_f32_e32 v38, 1.0, v38
	v_rcp_f32_e32 v38, v38
	s_nop 0
	v_mul_f32_e32 v28, v28, v38
	ds_write_b32 v3, v28 offset:16384
	s_waitcnt vmcnt(0)
	v_mul_f32_e32 v39, 0xbfb8aa3b, v29
	v_exp_f32_e32 v39, v39
	s_nop 0
	v_add_f32_e32 v39, 1.0, v39
	v_rcp_f32_e32 v39, v39
	s_nop 0
	v_mul_f32_e32 v29, v29, v39
	ds_write_b32 v3, v29 offset:18432

; __device__ __forceinline__ void phase_mod(const PP& p, float* sm) {
;     ...
;         const int l = it / 48, cb = it - l * 48, col = cb * 128 + 2 * lane;
;         const float* W = p.in[I_ADAW] + (size_t)l * 1024 * 6144 + col;
;         f32x2 a[5];
; #pragma unroll
;         for (int i = 0; i < 5; ++i) a[i] = (f32x2){0.f, 0.f};
; #pragma unroll 8
;         for (int k = w * 128; k < w * 128 + 128; ++k) {
;             const f32x2 wv = *(const f32x2*)(W + (size_t)k * 6144);
; #pragma unroll
;             for (int i = 0; i < 5; ++i) a[i] += sv[i * 1024 + k] * wv;
;         }
.LBB0_16:
	s_mul_hi_i32 s0, s10, 0x2aaaaaab
	ds_read_b64 v[10:11], v24
	s_lshr_b32 s1, s0, 31
	s_ashr_i32 s0, s0, 3
	s_add_i32 s6, s0, s1
	s_mul_i32 s7, s6, 0x1800
	v_subrev_u32_e32 v12, s7, v4
	v_ashrrev_i32_e32 v13, 31, v12
	s_waitcnt lgkmcnt(0)
	v_readfirstlane_b32 s1, v11
	v_readfirstlane_b32 s0, v10
	v_lshlrev_b64 v[12:13], 2, v[12:13]
	s_mov_b64 s[4:5], 0
	v_lshl_add_u64 v[10:11], s[0:1], 0, v[8:9]
	v_mad_i64_i32 v[12:13], s[0:1], s6, v25, v[12:13]
	v_lshl_add_u64 v[10:11], v[10:11], 0, v[12:13]
	v_mov_b32_e32 v27, v23
	v_mov_b32_e32 v12, 0
	v_mov_b32_e32 v13, v5
	v_mov_b32_e32 v14, 0
	v_mov_b32_e32 v15, v5
	v_mov_b32_e32 v16, 0
	v_mov_b32_e32 v17, v5
	v_mov_b32_e32 v18, 0
	v_mov_b32_e32 v19, v5
	v_mov_b32_e32 v20, 0
	v_mov_b32_e32 v21, v5
	v_mov_b32_e32 v120, v10
	v_mov_b32_e32 v121, v11
	s_mov_b64 s[0:1], 0x6000
	s_mov_b32 s4, 7
	global_load_dwordx2 v[68:69], v[120:121], off
	v_lshl_add_u64 v[120:121], v[120:121], 0, s[0:1]
	global_load_dwordx2 v[70:71], v[120:121], off
	v_lshl_add_u64 v[120:121], v[120:121], 0, s[0:1]
	global_load_dwordx2 v[72:73], v[120:121], off
	v_lshl_add_u64 v[120:121], v[120:121], 0, s[0:1]
	global_load_dwordx2 v[74:75], v[120:121], off
	v_lshl_add_u64 v[120:121], v[120:121], 0, s[0:1]
	global_load_dwordx2 v[76:77], v[120:121], off
	v_lshl_add_u64 v[120:121], v[120:121], 0, s[0:1]
	global_load_dwordx2 v[78:79], v[120:121], off
	v_lshl_add_u64 v[120:121], v[120:121], 0, s[0:1]
	global_load_dwordx2 v[80:81], v[120:121], off
	v_lshl_add_u64 v[120:121], v[120:121], 0, s[0:1]
	global_load_dwordx2 v[82:83], v[120:121], off
	v_lshl_add_u64 v[120:121], v[120:121], 0, s[0:1]
.Lmod_k:
	global_load_dwordx2 v[104:105], v[120:121], off
	v_lshl_add_u64 v[120:121], v[120:121], 0, s[0:1]
	global_load_dwordx2 v[106:107], v[120:121], off
	v_lshl_add_u64 v[120:121], v[120:121], 0, s[0:1]
	global_load_dwordx2 v[108:109], v[120:121], off
	v_lshl_add_u64 v[120:121], v[120:121], 0, s[0:1]
	global_load_dwordx2 v[110:111], v[120:121], off
	v_lshl_add_u64 v[120:121], v[120:121], 0, s[0:1]
	global_load_dwordx2 v[112:113], v[120:121], off
	v_lshl_add_u64 v[120:121], v[120:121], 0, s[0:1]
	global_load_dwordx2 v[114:115], v[120:121], off
	v_lshl_add_u64 v[120:121], v[120:121], 0, s[0:1]
	global_load_dwordx2 v[116:117], v[120:121], off
	v_lshl_add_u64 v[120:121], v[120:121], 0, s[0:1]
	global_load_dwordx2 v[118:119], v[120:121], off
	v_lshl_add_u64 v[120:121], v[120:121], 0, s[0:1]
	ds_read_b128 v[28:31], v27
	ds_read_b128 v[32:35], v27 offset:16
	ds_read_b128 v[36:39], v27 offset:4096
	ds_read_b128 v[40:43], v27 offset:4112
	ds_read_b128 v[44:47], v27 offset:8192
	ds_read_b128 v[48:51], v27 offset:8208
	ds_read_b128 v[52:55], v27 offset:12288
	ds_read_b128 v[56:59], v27 offset:12304
	ds_read_b128 v[60:63], v27 offset:16384
	ds_read_b128 v[64:67], v27 offset:16400
	s_waitcnt lgkmcnt(9)
	v_mov_b32_e32 v84, v31
	s_waitcnt lgkmcnt(7)
	v_mov_b32_e32 v86, v39
	s_waitcnt lgkmcnt(5)
	v_mov_b32_e32 v88, v47
	s_waitcnt lgkmcnt(3)
	v_mov_b32_e32 v90, v55
	s_waitcnt lgkmcnt(1)
	v_mov_b32_e32 v92, v63
	v_mov_b32_e32 v94, v35
	v_mov_b32_e32 v96, v43
	v_mov_b32_e32 v98, v51
	v_mov_b32_e32 v100, v59
	s_waitcnt lgkmcnt(0)
	v_mov_b32_e32 v102, v67
	v_add_u32_e32 v27, 32, v27
	s_waitcnt vmcnt(15)
	v_pk_fma_f32 v[14:15], v[68:69], v[28:29], v[14:15] op_sel_hi:[1,0,1]
	v_pk_fma_f32 v[16:17], v[68:69], v[36:37], v[16:17] op_sel_hi:[1,0,1]
	v_pk_fma_f32 v[18:19], v[68:69], v[44:45], v[18:19] op_sel_hi:[1,0,1]
	v_pk_fma_f32 v[20:21], v[68:69], v[52:53], v[20:21] op_sel_hi:[1,0,1]
	v_pk_fma_f32 v[12:13], v[68:69], v[60:61], v[12:13] op_sel_hi:[1,0,1]
	s_waitcnt vmcnt(14)
	v_pk_fma_f32 v[14:15], v[70:71], v[28:29], v[14:15] op_sel:[0,1,0]
	v_pk_fma_f32 v[16:17], v[70:71], v[36:37], v[16:17] op_sel:[0,1,0]
	v_pk_fma_f32 v[18:19], v[70:71], v[44:45], v[18:19] op_sel:[0,1,0]
	v_pk_fma_f32 v[20:21], v[70:71], v[52:53], v[20:21] op_sel:[0,1,0]
	v_pk_fma_f32 v[12:13], v[70:71], v[60:61], v[12:13] op_sel:[0,1,0]
	s_waitcnt vmcnt(13)
	v_pk_fma_f32 v[14:15], v[72:73], v[30:31], v[14:15] op_sel_hi:[1,0,1]
	v_pk_fma_f32 v[16:17], v[72:73], v[38:39], v[16:17] op_sel_hi:[1,0,1]
	v_pk_fma_f32 v[18:19], v[72:73], v[46:47], v[18:19] op_sel_hi:[1,0,1]
	v_pk_fma_f32 v[20:21], v[72:73], v[54:55], v[20:21] op_sel_hi:[1,0,1]
	v_pk_fma_f32 v[12:13], v[72:73], v[62:63], v[12:13] op_sel_hi:[1,0,1]
	s_waitcnt vmcnt(12)
	v_pk_fma_f32 v[14:15], v[74:75], v[84:85], v[14:15] op_sel_hi:[1,0,1]
	v_pk_fma_f32 v[16:17], v[74:75], v[86:87], v[16:17] op_sel_hi:[1,0,1]
	v_pk_fma_f32 v[18:19], v[74:75], v[88:89], v[18:19] op_sel_hi:[1,0,1]
	v_pk_fma_f32 v[20:21], v[74:75], v[90:91], v[20:21] op_sel_hi:[1,0,1]
	v_pk_fma_f32 v[12:13], v[74:75], v[92:93], v[12:13] op_sel_hi:[1,0,1]
	s_waitcnt vmcnt(11)
	v_pk_fma_f32 v[14:15], v[76:77], v[32:33], v[14:15] op_sel_hi:[1,0,1]
	v_pk_fma_f32 v[16:17], v[76:77], v[40:41], v[16:17] op_sel_hi:[1,0,1]
	v_pk_fma_f32 v[18:19], v[76:77], v[48:49], v[18:19] op_sel_hi:[1,0,1]
	v_pk_fma_f32 v[20:21], v[76:77], v[56:57], v[20:21] op_sel_hi:[1,0,1]
	v_pk_fma_f32 v[12:13], v[76:77], v[64:65], v[12:13] op_sel_hi:[1,0,1]
	s_waitcnt vmcnt(10)
	v_pk_fma_f32 v[14:15], v[78:79], v[32:33], v[14:15] op_sel:[0,1,0]
	v_pk_fma_f32 v[16:17], v[78:79], v[40:41], v[16:17] op_sel:[0,1,0]
	v_pk_fma_f32 v[18:19], v[78:79], v[48:49], v[18:19] op_sel:[0,1,0]
	v_pk_fma_f32 v[20:21], v[78:79], v[56:57], v[20:21] op_sel:[0,1,0]
	v_pk_fma_f32 v[12:13], v[78:79], v[64:65], v[12:13] op_sel:[0,1,0]
	s_waitcnt vmcnt(9)
; __device__ __forceinline__ void phase_mod(const PP& p, float* sm) {
;     ...
;         for (int k = w * 128; k < w * 128 + 128; ++k) {
;             const f32x2 wv = *(const f32x2*)(W + (size_t)k * 6144);
; #pragma unroll
;             for (int i = 0; i < 5; ++i) a[i] += sv[i * 1024 + k] * wv;
	v_pk_fma_f32 v[14:15], v[80:81], v[34:35], v[14:15] op_sel_hi:[1,0,1]
	v_pk_fma_f32 v[16:17], v[80:81], v[42:43], v[16:17] op_sel_hi:[1,0,1]
	v_pk_fma_f32 v[18:19], v[80:81], v[50:51], v[18:19] op_sel_hi:[1,0,1]
	v_pk_fma_f32 v[20:21], v[80:81], v[58:59], v[20:21] op_sel_hi:[1,0,1]
	v_pk_fma_f32 v[12:13], v[80:81], v[66:67], v[12:13] op_sel_hi:[1,0,1]
	s_waitcnt vmcnt(8)
	v_pk_fma_f32 v[14:15], v[82:83], v[94:95], v[14:15] op_sel_hi:[1,0,1]
	v_pk_fma_f32 v[16:17], v[82:83], v[96:97], v[16:17] op_sel_hi:[1,0,1]
	v_pk_fma_f32 v[18:19], v[82:83], v[98:99], v[18:19] op_sel_hi:[1,0,1]
	v_pk_fma_f32 v[20:21], v[82:83], v[100:101], v[20:21] op_sel_hi:[1,0,1]
	v_pk_fma_f32 v[12:13], v[82:83], v[102:103], v[12:13] op_sel_hi:[1,0,1]
	global_load_dwordx2 v[68:69], v[120:121], off
	v_lshl_add_u64 v[120:121], v[120:121], 0, s[0:1]
	global_load_dwordx2 v[70:71], v[120:121], off
	v_lshl_add_u64 v[120:121], v[120:121], 0, s[0:1]
	global_load_dwordx2 v[72:73], v[120:121], off
	v_lshl_add_u64 v[120:121], v[120:121], 0, s[0:1]
	global_load_dwordx2 v[74:75], v[120:121], off
	v_lshl_add_u64 v[120:121], v[120:121], 0, s[0:1]
	global_load_dwordx2 v[76:77], v[120:121], off
	v_lshl_add_u64 v[120:121], v[120:121], 0, s[0:1]
	global_load_dwordx2 v[78:79], v[120:121], off
	v_lshl_add_u64 v[120:121], v[120:121], 0, s[0:1]
	global_load_dwordx2 v[80:81], v[120:121], off
	v_lshl_add_u64 v[120:121], v[120:121], 0, s[0:1]
	global_load_dwordx2 v[82:83], v[120:121], off
	v_lshl_add_u64 v[120:121], v[120:121], 0, s[0:1]
	ds_read_b128 v[28:31], v27
	ds_read_b128 v[32:35], v27 offset:16
	ds_read_b128 v[36:39], v27 offset:4096
	ds_read_b128 v[40:43], v27 offset:4112
	ds_read_b128 v[44:47], v27 offset:8192
	ds_read_b128 v[48:51], v27 offset:8208
	ds_read_b128 v[52:55], v27 offset:12288
	ds_read_b128 v[56:59], v27 offset:12304
	ds_read_b128 v[60:63], v27 offset:16384
	ds_read_b128 v[64:67], v27 offset:16400
	s_waitcnt lgkmcnt(9)
	v_mov_b32_e32 v84, v31
	s_waitcnt lgkmcnt(7)
	v_mov_b32_e32 v86, v39
	s_waitcnt lgkmcnt(5)
	v_mov_b32_e32 v88, v47
	s_waitcnt lgkmcnt(3)
	v_mov_b32_e32 v90, v55
	s_waitcnt lgkmcnt(1)
	v_mov_b32_e32 v92, v63
	v_mov_b32_e32 v94, v35
	v_mov_b32_e32 v96, v43
	v_mov_b32_e32 v98, v51
	v_mov_b32_e32 v100, v59
	s_waitcnt lgkmcnt(0)
	v_mov_b32_e32 v102, v67
	v_add_u32_e32 v27, 32, v27
	s_waitcnt vmcnt(15)
	v_pk_fma_f32 v[14:15], v[104:105], v[28:29], v[14:15] op_sel_hi:[1,0,1]
	v_pk_fma_f32 v[16:17], v[104:105], v[36:37], v[16:17] op_sel_hi:[1,0,1]
	v_pk_fma_f32 v[18:19], v[104:105], v[44:45], v[18:19] op_sel_hi:[1,0,1]
	v_pk_fma_f32 v[20:21], v[104:105], v[52:53], v[20:21] op_sel_hi:[1,0,1]
	v_pk_fma_f32 v[12:13], v[104:105], v[60:61], v[12:13] op_sel_hi:[1,0,1]
	s_waitcnt vmcnt(14)
	v_pk_fma_f32 v[14:15], v[106:107], v[28:29], v[14:15] op_sel:[0,1,0]
	v_pk_fma_f32 v[16:17], v[106:107], v[36:37], v[16:17] op_sel:[0,1,0]
	v_pk_fma_f32 v[18:19], v[106:107], v[44:45], v[18:19] op_sel:[0,1,0]
	v_pk_fma_f32 v[20:21], v[106:107], v[52:53], v[20:21] op_sel:[0,1,0]
	v_pk_fma_f32 v[12:13], v[106:107], v[60:61], v[12:13] op_sel:[0,1,0]
	s_waitcnt vmcnt(13)
	v_pk_fma_f32 v[14:15], v[108:109], v[30:31], v[14:15] op_sel_hi:[1,0,1]
	v_pk_fma_f32 v[16:17], v[108:109], v[38:39], v[16:17] op_sel_hi:[1,0,1]
	v_pk_fma_f32 v[18:19], v[108:109], v[46:47], v[18:19] op_sel_hi:[1,0,1]
	v_pk_fma_f32 v[20:21], v[108:109], v[54:55], v[20:21] op_sel_hi:[1,0,1]
	v_pk_fma_f32 v[12:13], v[108:109], v[62:63], v[12:13] op_sel_hi:[1,0,1]
	s_waitcnt vmcnt(12)
	v_pk_fma_f32 v[14:15], v[110:111], v[84:85], v[14:15] op_sel_hi:[1,0,1]
	v_pk_fma_f32 v[16:17], v[110:111], v[86:87], v[16:17] op_sel_hi:[1,0,1]
	v_pk_fma_f32 v[18:19], v[110:111], v[88:89], v[18:19] op_sel_hi:[1,0,1]
	v_pk_fma_f32 v[20:21], v[110:111], v[90:91], v[20:21] op_sel_hi:[1,0,1]
	v_pk_fma_f32 v[12:13], v[110:111], v[92:93], v[12:13] op_sel_hi:[1,0,1]
	s_waitcnt vmcnt(11)
	v_pk_fma_f32 v[14:15], v[112:113], v[32:33], v[14:15] op_sel_hi:[1,0,1]
	v_pk_fma_f32 v[16:17], v[112:113], v[40:41], v[16:17] op_sel_hi:[1,0,1]
	v_pk_fma_f32 v[18:19], v[112:113], v[48:49], v[18:19] op_sel_hi:[1,0,1]
	v_pk_fma_f32 v[20:21], v[112:113], v[56:57], v[20:21] op_sel_hi:[1,0,1]
	v_pk_fma_f32 v[12:13], v[112:113], v[64:65], v[12:13] op_sel_hi:[1,0,1]
	s_waitcnt vmcnt(10)
	v_pk_fma_f32 v[14:15], v[114:115], v[32:33], v[14:15] op_sel:[0,1,0]
	v_pk_fma_f32 v[16:17], v[114:115], v[40:41], v[16:17] op_sel:[0,1,0]
	v_pk_fma_f32 v[18:19], v[114:115], v[48:49], v[18:19] op_sel:[0,1,0]
	v_pk_fma_f32 v[20:21], v[114:115], v[56:57], v[20:21] op_sel:[0,1,0]
	v_pk_fma_f32 v[12:13], v[114:115], v[64:65], v[12:13] op_sel:[0,1,0]
	s_waitcnt vmcnt(9)
	v_pk_fma_f32 v[14:15], v[116:117], v[34:35], v[14:15] op_sel_hi:[1,0,1]
	v_pk_fma_f32 v[16:17], v[116:117], v[42:43], v[16:17] op_sel_hi:[1,0,1]
	v_pk_fma_f32 v[18:19], v[116:117], v[50:51], v[18:19] op_sel_hi:[1,0,1]
	v_pk_fma_f32 v[20:21], v[116:117], v[58:59], v[20:21] op_sel_hi:[1,0,1]
	v_pk_fma_f32 v[12:13], v[116:117], v[66:67], v[12:13] op_sel_hi:[1,0,1]
	s_waitcnt vmcnt(8)
	v_pk_fma_f32 v[14:15], v[118:119], v[94:95], v[14:15] op_sel_hi:[1,0,1]
	v_pk_fma_f32 v[16:17], v[118:119], v[96:97], v[16:17] op_sel_hi:[1,0,1]
	v_pk_fma_f32 v[18:19], v[118:119], v[98:99], v[18:19] op_sel_hi:[1,0,1]
	v_pk_fma_f32 v[20:21], v[118:119], v[100:101], v[20:21] op_sel_hi:[1,0,1]
	v_pk_fma_f32 v[12:13], v[118:119], v[102:103], v[12:13] op_sel_hi:[1,0,1]
	s_add_i32 s4, s4, -1
	s_cmp_eq_u32 s4, 0
	s_cbranch_scc0 .Lmod_k
; __device__ __forceinline__ void phase_mod(const PP& p, float* sm) {
;     ...
;         for (int k = w * 128; k < w * 128 + 128; ++k) {
;             const f32x2 wv = *(const f32x2*)(W + (size_t)k * 6144);
; #pragma unroll
;             for (int i = 0; i < 5; ++i) a[i] += sv[i * 1024 + k] * wv;
	global_load_dwordx2 v[104:105], v[120:121], off
	v_lshl_add_u64 v[120:121], v[120:121], 0, s[0:1]
	global_load_dwordx2 v[106:107], v[120:121], off
	v_lshl_add_u64 v[120:121], v[120:121], 0, s[0:1]
	global_load_dwordx2 v[108:109], v[120:121], off
	v_lshl_add_u64 v[120:121], v[120:121], 0, s[0:1]
	global_load_dwordx2 v[110:111], v[120:121], off
	v_lshl_add_u64 v[120:121], v[120:121], 0, s[0:1]
	global_load_dwordx2 v[112:113], v[120:121], off
	v_lshl_add_u64 v[120:121], v[120:121], 0, s[0:1]
	global_load_dwordx2 v[114:115], v[120:121], off
	v_lshl_add_u64 v[120:121], v[120:121], 0, s[0:1]
	global_load_dwordx2 v[116:117], v[120:121], off
	v_lshl_add_u64 v[120:121], v[120:121], 0, s[0:1]
	global_load_dwordx2 v[118:119], v[120:121], off
	v_lshl_add_u64 v[120:121], v[120:121], 0, s[0:1]
	ds_read_b128 v[28:31], v27
	ds_read_b128 v[32:35], v27 offset:16
	ds_read_b128 v[36:39], v27 offset:4096
	ds_read_b128 v[40:43], v27 offset:4112
	ds_read_b128 v[44:47], v27 offset:8192
	ds_read_b128 v[48:51], v27 offset:8208
	ds_read_b128 v[52:55], v27 offset:12288
	ds_read_b128 v[56:59], v27 offset:12304
	ds_read_b128 v[60:63], v27 offset:16384
	ds_read_b128 v[64:67], v27 offset:16400
	s_waitcnt lgkmcnt(9)
	v_mov_b32_e32 v84, v31
	s_waitcnt lgkmcnt(7)
	v_mov_b32_e32 v86, v39
	s_waitcnt lgkmcnt(5)
	v_mov_b32_e32 v88, v47
	s_waitcnt lgkmcnt(3)
	v_mov_b32_e32 v90, v55
	s_waitcnt lgkmcnt(1)
	v_mov_b32_e32 v92, v63
	v_mov_b32_e32 v94, v35
	v_mov_b32_e32 v96, v43
	v_mov_b32_e32 v98, v51
	v_mov_b32_e32 v100, v59
	s_waitcnt lgkmcnt(0)
	v_mov_b32_e32 v102, v67
	v_add_u32_e32 v27, 32, v27
	s_waitcnt vmcnt(15)
	v_pk_fma_f32 v[14:15], v[68:69], v[28:29], v[14:15] op_sel_hi:[1,0,1]
	v_pk_fma_f32 v[16:17], v[68:69], v[36:37], v[16:17] op_sel_hi:[1,0,1]
	v_pk_fma_f32 v[18:19], v[68:69], v[44:45], v[18:19] op_sel_hi:[1,0,1]
	v_pk_fma_f32 v[20:21], v[68:69], v[52:53], v[20:21] op_sel_hi:[1,0,1]
	v_pk_fma_f32 v[12:13], v[68:69], v[60:61], v[12:13] op_sel_hi:[1,0,1]
	s_waitcnt vmcnt(14)
	v_pk_fma_f32 v[14:15], v[70:71], v[28:29], v[14:15] op_sel:[0,1,0]
	v_pk_fma_f32 v[16:17], v[70:71], v[36:37], v[16:17] op_sel:[0,1,0]
	v_pk_fma_f32 v[18:19], v[70:71], v[44:45], v[18:19] op_sel:[0,1,0]
	v_pk_fma_f32 v[20:21], v[70:71], v[52:53], v[20:21] op_sel:[0,1,0]
	v_pk_fma_f32 v[12:13], v[70:71], v[60:61], v[12:13] op_sel:[0,1,0]
	s_waitcnt vmcnt(13)
	v_pk_fma_f32 v[14:15], v[72:73], v[30:31], v[14:15] op_sel_hi:[1,0,1]
	v_pk_fma_f32 v[16:17], v[72:73], v[38:39], v[16:17] op_sel_hi:[1,0,1]
	v_pk_fma_f32 v[18:19], v[72:73], v[46:47], v[18:19] op_sel_hi:[1,0,1]
	v_pk_fma_f32 v[20:21], v[72:73], v[54:55], v[20:21] op_sel_hi:[1,0,1]
	v_pk_fma_f32 v[12:13], v[72:73], v[62:63], v[12:13] op_sel_hi:[1,0,1]
	s_waitcnt vmcnt(12)
	v_pk_fma_f32 v[14:15], v[74:75], v[84:85], v[14:15] op_sel_hi:[1,0,1]
	v_pk_fma_f32 v[16:17], v[74:75], v[86:87], v[16:17] op_sel_hi:[1,0,1]
	v_pk_fma_f32 v[18:19], v[74:75], v[88:89], v[18:19] op_sel_hi:[1,0,1]
	v_pk_fma_f32 v[20:21], v[74:75], v[90:91], v[20:21] op_sel_hi:[1,0,1]
	v_pk_fma_f32 v[12:13], v[74:75], v[92:93], v[12:13] op_sel_hi:[1,0,1]
	s_waitcnt vmcnt(11)
	v_pk_fma_f32 v[14:15], v[76:77], v[32:33], v[14:15] op_sel_hi:[1,0,1]
	v_pk_fma_f32 v[16:17], v[76:77], v[40:41], v[16:17] op_sel_hi:[1,0,1]
	v_pk_fma_f32 v[18:19], v[76:77], v[48:49], v[18:19] op_sel_hi:[1,0,1]
	v_pk_fma_f32 v[20:21], v[76:77], v[56:57], v[20:21] op_sel_hi:[1,0,1]
	v_pk_fma_f32 v[12:13], v[76:77], v[64:65], v[12:13] op_sel_hi:[1,0,1]
	s_waitcnt vmcnt(10)
	v_pk_fma_f32 v[14:15], v[78:79], v[32:33], v[14:15] op_sel:[0,1,0]
	v_pk_fma_f32 v[16:17], v[78:79], v[40:41], v[16:17] op_sel:[0,1,0]
	v_pk_fma_f32 v[18:19], v[78:79], v[48:49], v[18:19] op_sel:[0,1,0]
	v_pk_fma_f32 v[20:21], v[78:79], v[56:57], v[20:21] op_sel:[0,1,0]
	v_pk_fma_f32 v[12:13], v[78:79], v[64:65], v[12:13] op_sel:[0,1,0]
	s_waitcnt vmcnt(9)
	v_pk_fma_f32 v[14:15], v[80:81], v[34:35], v[14:15] op_sel_hi:[1,0,1]
	v_pk_fma_f32 v[16:17], v[80:81], v[42:43], v[16:17] op_sel_hi:[1,0,1]
	v_pk_fma_f32 v[18:19], v[80:81], v[50:51], v[18:19] op_sel_hi:[1,0,1]
	v_pk_fma_f32 v[20:21], v[80:81], v[58:59], v[20:21] op_sel_hi:[1,0,1]
	v_pk_fma_f32 v[12:13], v[80:81], v[66:67], v[12:13] op_sel_hi:[1,0,1]
	s_waitcnt vmcnt(8)
; __device__ __forceinline__ void phase_mod(const PP& p, float* sm) {
;     ...
;         for (int k = w * 128; k < w * 128 + 128; ++k) {
;             const f32x2 wv = *(const f32x2*)(W + (size_t)k * 6144);
; #pragma unroll
;             for (int i = 0; i < 5; ++i) a[i] += sv[i * 1024 + k] * wv;
;         }
; #pragma unroll
;         for (int i = 0; i < 5; ++i) { part[(w * 5 + i) * 128 + 2 * lane] = a[i].x; part[(w * 5 + i) * 128 + 2 * lane + 1] = a[i].y; }
;         __syncthreads();
;         for (int o = tid; o < 640; o += 512) { const int i = o >> 7, cc = o & 127; float s = 0.f;
; #pragma unroll
;             for (int ww = 0; ww < 8; ++ww) s += part[(ww * 5 + i) * 128 + cc];
;             mod[((size_t)l * 5 + i) * 6144 + cb * 128 + cc] = s + p.in[I_ADAB][l * 6144 + cb * 128 + cc]; }
	v_pk_fma_f32 v[14:15], v[82:83], v[94:95], v[14:15] op_sel_hi:[1,0,1]
	v_pk_fma_f32 v[16:17], v[82:83], v[96:97], v[16:17] op_sel_hi:[1,0,1]
	v_pk_fma_f32 v[18:19], v[82:83], v[98:99], v[18:19] op_sel_hi:[1,0,1]
	v_pk_fma_f32 v[20:21], v[82:83], v[100:101], v[20:21] op_sel_hi:[1,0,1]
	v_pk_fma_f32 v[12:13], v[82:83], v[102:103], v[12:13] op_sel_hi:[1,0,1]
	ds_read_b128 v[28:31], v27
	ds_read_b128 v[32:35], v27 offset:16
	ds_read_b128 v[36:39], v27 offset:4096
	ds_read_b128 v[40:43], v27 offset:4112
	ds_read_b128 v[44:47], v27 offset:8192
	ds_read_b128 v[48:51], v27 offset:8208
	ds_read_b128 v[52:55], v27 offset:12288
	ds_read_b128 v[56:59], v27 offset:12304
	ds_read_b128 v[60:63], v27 offset:16384
	ds_read_b128 v[64:67], v27 offset:16400
	s_waitcnt lgkmcnt(9)
	v_mov_b32_e32 v84, v31
	s_waitcnt lgkmcnt(7)
	v_mov_b32_e32 v86, v39
	s_waitcnt lgkmcnt(5)
	v_mov_b32_e32 v88, v47
	s_waitcnt lgkmcnt(3)
	v_mov_b32_e32 v90, v55
	s_waitcnt lgkmcnt(1)
	v_mov_b32_e32 v92, v63
	v_mov_b32_e32 v94, v35
	v_mov_b32_e32 v96, v43
	v_mov_b32_e32 v98, v51
	v_mov_b32_e32 v100, v59
	s_waitcnt lgkmcnt(0)
	v_mov_b32_e32 v102, v67
	v_add_u32_e32 v27, 32, v27
	s_waitcnt vmcnt(7)
	v_pk_fma_f32 v[14:15], v[104:105], v[28:29], v[14:15] op_sel_hi:[1,0,1]
	v_pk_fma_f32 v[16:17], v[104:105], v[36:37], v[16:17] op_sel_hi:[1,0,1]
	v_pk_fma_f32 v[18:19], v[104:105], v[44:45], v[18:19] op_sel_hi:[1,0,1]
	v_pk_fma_f32 v[20:21], v[104:105], v[52:53], v[20:21] op_sel_hi:[1,0,1]
	v_pk_fma_f32 v[12:13], v[104:105], v[60:61], v[12:13] op_sel_hi:[1,0,1]
	s_waitcnt vmcnt(6)
	v_pk_fma_f32 v[14:15], v[106:107], v[28:29], v[14:15] op_sel:[0,1,0]
	v_pk_fma_f32 v[16:17], v[106:107], v[36:37], v[16:17] op_sel:[0,1,0]
	v_pk_fma_f32 v[18:19], v[106:107], v[44:45], v[18:19] op_sel:[0,1,0]
	v_pk_fma_f32 v[20:21], v[106:107], v[52:53], v[20:21] op_sel:[0,1,0]
	v_pk_fma_f32 v[12:13], v[106:107], v[60:61], v[12:13] op_sel:[0,1,0]
	s_waitcnt vmcnt(5)
	v_pk_fma_f32 v[14:15], v[108:109], v[30:31], v[14:15] op_sel_hi:[1,0,1]
	v_pk_fma_f32 v[16:17], v[108:109], v[38:39], v[16:17] op_sel_hi:[1,0,1]
	v_pk_fma_f32 v[18:19], v[108:109], v[46:47], v[18:19] op_sel_hi:[1,0,1]
	v_pk_fma_f32 v[20:21], v[108:109], v[54:55], v[20:21] op_sel_hi:[1,0,1]
	v_pk_fma_f32 v[12:13], v[108:109], v[62:63], v[12:13] op_sel_hi:[1,0,1]
	s_waitcnt vmcnt(4)
	v_pk_fma_f32 v[14:15], v[110:111], v[84:85], v[14:15] op_sel_hi:[1,0,1]
	v_pk_fma_f32 v[16:17], v[110:111], v[86:87], v[16:17] op_sel_hi:[1,0,1]
	v_pk_fma_f32 v[18:19], v[110:111], v[88:89], v[18:19] op_sel_hi:[1,0,1]
	v_pk_fma_f32 v[20:21], v[110:111], v[90:91], v[20:21] op_sel_hi:[1,0,1]
	v_pk_fma_f32 v[12:13], v[110:111], v[92:93], v[12:13] op_sel_hi:[1,0,1]
	s_waitcnt vmcnt(3)
	v_pk_fma_f32 v[14:15], v[112:113], v[32:33], v[14:15] op_sel_hi:[1,0,1]
	v_pk_fma_f32 v[16:17], v[112:113], v[40:41], v[16:17] op_sel_hi:[1,0,1]
	v_pk_fma_f32 v[18:19], v[112:113], v[48:49], v[18:19] op_sel_hi:[1,0,1]
	v_pk_fma_f32 v[20:21], v[112:113], v[56:57], v[20:21] op_sel_hi:[1,0,1]
	v_pk_fma_f32 v[12:13], v[112:113], v[64:65], v[12:13] op_sel_hi:[1,0,1]
	s_waitcnt vmcnt(2)
	v_pk_fma_f32 v[14:15], v[114:115], v[32:33], v[14:15] op_sel:[0,1,0]
	v_pk_fma_f32 v[16:17], v[114:115], v[40:41], v[16:17] op_sel:[0,1,0]
	v_pk_fma_f32 v[18:19], v[114:115], v[48:49], v[18:19] op_sel:[0,1,0]
	v_pk_fma_f32 v[20:21], v[114:115], v[56:57], v[20:21] op_sel:[0,1,0]
	v_pk_fma_f32 v[12:13], v[114:115], v[64:65], v[12:13] op_sel:[0,1,0]
	s_waitcnt vmcnt(1)
	v_pk_fma_f32 v[14:15], v[116:117], v[34:35], v[14:15] op_sel_hi:[1,0,1]
	v_pk_fma_f32 v[16:17], v[116:117], v[42:43], v[16:17] op_sel_hi:[1,0,1]
	v_pk_fma_f32 v[18:19], v[116:117], v[50:51], v[18:19] op_sel_hi:[1,0,1]
	v_pk_fma_f32 v[20:21], v[116:117], v[58:59], v[20:21] op_sel_hi:[1,0,1]
	v_pk_fma_f32 v[12:13], v[116:117], v[66:67], v[12:13] op_sel_hi:[1,0,1]
	s_waitcnt vmcnt(0)
	v_pk_fma_f32 v[14:15], v[118:119], v[94:95], v[14:15] op_sel_hi:[1,0,1]
	v_pk_fma_f32 v[16:17], v[118:119], v[96:97], v[16:17] op_sel_hi:[1,0,1]
	v_pk_fma_f32 v[18:19], v[118:119], v[98:99], v[18:19] op_sel_hi:[1,0,1]
	v_pk_fma_f32 v[20:21], v[118:119], v[100:101], v[20:21] op_sel_hi:[1,0,1]
	v_pk_fma_f32 v[12:13], v[118:119], v[102:103], v[12:13] op_sel_hi:[1,0,1]
	ds_write2st64_b64 v26, v[14:15], v[16:17] offset0:40 offset1:41
	ds_write2st64_b64 v26, v[18:19], v[20:21] offset0:42 offset1:43
	ds_write_b64 v26, v[12:13] offset:22528
	s_waitcnt lgkmcnt(0)
	s_barrier
	s_and_saveexec_b64 s[4:5], vcc
	s_cbranch_execz .LBB0_15
	s_mul_i32 s0, s6, 0xffffffd0
	v_mov_b32_e32 v10, s28
	s_add_i32 s0, s0, s10
	ds_read_b64 v[10:11], v10
	s_lshl_b32 s0, s0, 7
	s_add_i32 s8, s0, s7
	s_ashr_i32 s1, s0, 31
	v_or_b32_e32 v12, s8, v3
	s_mul_hi_i32 s7, s6, 5
	s_mul_i32 s6, s6, 5
	v_ashrrev_i32_e32 v13, 31, v12
	v_lshl_add_u64 v[14:15], s[0:1], 2, v[6:7]
	s_mov_b64 s[8:9], 0
	v_mov_b32_e32 v16, v2
